# adds: SGU spatial bias loaded once per workgroup and reused across its items
# baseline (speedup 1.0000x reference)
; #define LAS __attribute__((address_space(3)))
; __device__ __forceinline__ float bflo(unsigned w) { return __uint_as_float(w << 16); }
; __device__ __forceinline__ float bfhi(unsigned w) { return __uint_as_float(w & 0xffff0000u); }
; __device__ __forceinline__ void sgu_item(LAS unsigned char* lds, const bf16_t* z, const float* lng, const float* lnb, const float* wsg, const float* bsg, bf16_t* cat, int b, int c, int g) {
;     ...
; #pragma unroll
;     for (int i = 0; i < 4; ++i) { const int t = t0 + quad * 4 + i; const float bias = bsg[g * 128 + t];
; #pragma unroll
;         for (int nt = 0; nt < 8; ++nt) ob[t * 132 + nt * 16 + lq] = acc[nt][i] + bias; }
;     __syncthreads();
;     {   bf16_t* op = cat + (row0 + p) * DM + 1024 + g * 128 + part * 32;
; #pragma unroll
;         for (int q = 0; q < 4; ++q) { const f32x4 m0 = *(LAS const f32x4*)(ob + p * 132 + part * 32 + q * 8), m1 = *(LAS const f32x4*)(ob + p * 132 + part * 32 + q * 8 + 4);
;             const f32x4 u0 = (f32x4){bflo(uw[q].x), bfhi(uw[q].x), bflo(uw[q].y), bfhi(uw[q].y)}, u1 = (f32x4){bflo(uw[q].z), bfhi(uw[q].z), bflo(uw[q].w), bfhi(uw[q].w)};
;             *(u32x4*)(op + q * 8) = pack8(u0 * m0, u1 * m1); }
;     }
;     __syncthreads();
.LBB0_1667:
	v_lshl_or_b32 v26, v71, 2, s18
	s_add_u32 s2, s8, s6
	v_add_u32_e32 v18, s17, v26
	s_addc_u32 s3, s9, s7
	v_ashrrev_i32_e32 v19, 31, v18
	v_lshl_add_u64 v[18:19], v[18:19], 2, s[2:3]
	s_and_b32 s2, s48, 7
	s_cbranch_scc1 .Lmy_b_do
	s_cmp_lg_u32 s16, s71
	s_cbranch_scc0 .Lmy_b_do
	v_mov_b64_e32 v[18:19], v[222:223]
	v_mov_b64_e32 v[20:21], v[224:225]
	s_branch .Lmy_b_skip
.Lmy_b_do:
	global_load_dwordx4 v[18:21], v[18:19], off
.Lmy_b_skip:
	s_movk_i32 s2, 0x210
	v_lshlrev_b32_e32 v27, 2, v70
	v_mul_lo_u32 v26, v26, s2
	v_add3_u32 v26, 0, v27, v26
	v_add_u32_e32 v28, 0x8800, v26
	s_lshl_b32 s56, s17, 1
	v_and_b32_e32 v29, 0xffff0000, v14
	s_add_i32 s16, s16, s48
	s_waitcnt vmcnt(0)
	v_mov_b64_e32 v[222:223], v[18:19]
	v_mov_b64_e32 v[224:225], v[20:21]
	v_add_f32_e32 v27, v18, v30
	v_add_f32_e32 v22, v22, v18
	ds_write2_b32 v28, v27, v22 offset1:16
	v_add_f32_e32 v22, v50, v18
	v_add_f32_e32 v27, v46, v18
	ds_write2_b32 v28, v22, v27 offset0:32 offset1:48
	v_add_f32_e32 v22, v58, v18
	v_add_f32_e32 v27, v54, v18
	ds_write2_b32 v28, v22, v27 offset0:64 offset1:80
	v_add_f32_e32 v22, v62, v18
	v_add_f32_e32 v18, v38, v18
	ds_write2_b32 v28, v22, v18 offset0:96 offset1:112
	v_add_f32_e32 v18, v31, v19
	v_add_f32_e32 v22, v23, v19
	ds_write2_b32 v28, v18, v22 offset0:132 offset1:148
	v_add_f32_e32 v18, v51, v19
	v_add_f32_e32 v22, v47, v19
	ds_write2_b32 v28, v18, v22 offset0:164 offset1:180
	v_add_f32_e32 v18, v59, v19
	v_add_f32_e32 v22, v55, v19
	ds_write2_b32 v28, v18, v22 offset0:196 offset1:212
	v_add_f32_e32 v18, v63, v19
	v_add_f32_e32 v19, v39, v19
	ds_write2_b32 v28, v18, v19 offset0:228 offset1:244
	v_add_f32_e32 v18, v32, v20
	v_add_f32_e32 v19, v24, v20
	v_add_u32_e32 v22, 0x8c00, v26
	ds_write2_b32 v22, v18, v19 offset0:8 offset1:24
	v_add_f32_e32 v18, v52, v20
	v_add_f32_e32 v19, v48, v20
	ds_write2_b32 v22, v18, v19 offset0:40 offset1:56
	v_add_f32_e32 v18, v60, v20
	v_add_f32_e32 v19, v56, v20
	ds_write2_b32 v22, v18, v19 offset0:72 offset1:88
	v_add_f32_e32 v18, v64, v20
	v_add_f32_e32 v19, v40, v20
	ds_write2_b32 v22, v18, v19 offset0:104 offset1:120
	v_add_f32_e32 v18, v33, v21
	v_add_f32_e32 v19, v25, v21
	ds_write2_b32 v22, v18, v19 offset0:140 offset1:156
	v_add_f32_e32 v18, v53, v21
	v_add_f32_e32 v19, v49, v21
	ds_write2_b32 v22, v18, v19 offset0:172 offset1:188
	v_add_f32_e32 v18, v61, v21
	v_add_f32_e32 v19, v57, v21
	ds_write2_b32 v22, v18, v19 offset0:204 offset1:220
	v_add_f32_e32 v18, v65, v21
	v_add_f32_e32 v19, v41, v21
	ds_write2_b32 v22, v18, v19 offset0:236 offset1:252
	v_lshlrev_b64 v[18:19], 12, v[68:69]
	v_lshl_add_u64 v[18:19], s[94:95], 0, v[18:19]
	v_lshl_add_u64 v[18:19], v[18:19], 0, s[56:57]
	v_lshl_add_u64 v[22:23], v[18:19], 0, v[8:9]
	v_mul_lo_u32 v8, v66, s2
	v_lshlrev_b32_e32 v18, 2, v67
	v_add3_u32 v8, 0, v8, v18
	s_waitcnt lgkmcnt(0)
	s_barrier
	ds_read_b128 v[18:21], v8 offset:34816
	ds_read_b128 v[24:27], v8 offset:34832
	v_lshlrev_b32_e32 v28, 16, v14
	v_lshlrev_b32_e32 v14, 16, v15
	v_and_b32_e32 v15, 0xffff0000, v15
	v_lshlrev_b32_e32 v30, 16, v16
	v_and_b32_e32 v31, 0xffff0000, v16
	v_lshlrev_b32_e32 v16, 16, v17
	v_and_b32_e32 v17, 0xffff0000, v17
	s_waitcnt lgkmcnt(1)
	v_pk_mul_f32 v[20:21], v[20:21], v[14:15]
	v_pk_mul_f32 v[14:15], v[18:19], v[28:29]
	s_waitcnt lgkmcnt(0)
	v_pk_mul_f32 v[18:19], v[26:27], v[16:17]
	v_pk_mul_f32 v[16:17], v[24:25], v[30:31]
	v_cvt_pk_bf16_f32 v14, v14, v15
	v_cvt_pk_bf16_f32 v15, v20, v21
	v_lshlrev_b32_e32 v24, 16, v10
	v_cvt_pk_bf16_f32 v16, v16, v17
	v_cvt_pk_bf16_f32 v17, v18, v19
	global_store_dwordx4 v[22:23], v[14:17], off offset:2048
	ds_read_b128 v[18:21], v8 offset:34848
	ds_read_b128 v[14:17], v8 offset:34864
	v_and_b32_e32 v25, 0xffff0000, v10
	v_lshlrev_b32_e32 v10, 16, v11
	v_and_b32_e32 v11, 0xffff0000, v11
	v_lshlrev_b32_e32 v26, 16, v12
	v_and_b32_e32 v27, 0xffff0000, v12
	v_lshlrev_b32_e32 v12, 16, v13
	v_and_b32_e32 v13, 0xffff0000, v13
	s_waitcnt lgkmcnt(1)
	v_pk_mul_f32 v[20:21], v[20:21], v[10:11]
	v_pk_mul_f32 v[10:11], v[18:19], v[24:25]
	s_waitcnt lgkmcnt(0)
	v_pk_mul_f32 v[16:17], v[16:17], v[12:13]
	v_pk_mul_f32 v[12:13], v[14:15], v[26:27]
	v_cvt_pk_bf16_f32 v10, v10, v11
	v_cvt_pk_bf16_f32 v11, v20, v21
	v_lshlrev_b32_e32 v18, 16, v4
	v_cvt_pk_bf16_f32 v12, v12, v13
	v_cvt_pk_bf16_f32 v13, v16, v17
	global_store_dwordx4 v[22:23], v[10:13], off offset:2064
	ds_read_b128 v[10:13], v8 offset:34880
	ds_read_b128 v[14:17], v8 offset:34896
	v_and_b32_e32 v19, 0xffff0000, v4
	v_lshlrev_b32_e32 v4, 16, v5
	v_and_b32_e32 v5, 0xffff0000, v5
	v_lshlrev_b32_e32 v20, 16, v6
	v_and_b32_e32 v21, 0xffff0000, v6
	v_lshlrev_b32_e32 v6, 16, v7
	v_and_b32_e32 v7, 0xffff0000, v7
	s_waitcnt lgkmcnt(1)
	v_pk_mul_f32 v[12:13], v[12:13], v[4:5]
	v_pk_mul_f32 v[4:5], v[10:11], v[18:19]
	s_waitcnt lgkmcnt(0)
	v_pk_mul_f32 v[10:11], v[16:17], v[6:7]
	v_pk_mul_f32 v[6:7], v[14:15], v[20:21]
	v_cvt_pk_bf16_f32 v4, v4, v5
	v_cvt_pk_bf16_f32 v5, v12, v13
	v_readlane_b32 s2, v255, 16
	v_cvt_pk_bf16_f32 v6, v6, v7
	v_cvt_pk_bf16_f32 v7, v10, v11
	global_store_dwordx4 v[22:23], v[4:7], off offset:2080
	ds_read_b128 v[4:7], v8 offset:34912
	ds_read_b128 v[10:13], v8 offset:34928
	s_add_i32 s15, s15, s2
	v_readlane_b32 s2, v255, 18
	v_lshlrev_b32_e32 v14, 16, v0
	v_and_b32_e32 v15, 0xffff0000, v0
	v_lshlrev_b32_e32 v0, 16, v1
	v_and_b32_e32 v1, 0xffff0000, v1
	v_lshlrev_b32_e32 v16, 16, v2
	v_and_b32_e32 v17, 0xffff0000, v2
	v_lshlrev_b32_e32 v2, 16, v3
	v_and_b32_e32 v3, 0xffff0000, v3
	s_add_i32 s14, s14, s2
	s_waitcnt lgkmcnt(1)
	v_pk_mul_f32 v[6:7], v[6:7], v[0:1]
	v_pk_mul_f32 v[0:1], v[4:5], v[14:15]
	s_waitcnt lgkmcnt(0)
	v_pk_mul_f32 v[4:5], v[12:13], v[2:3]
	v_pk_mul_f32 v[2:3], v[10:11], v[16:17]
	s_cmpk_gt_i32 s16, 0x3ff
	v_cvt_pk_bf16_f32 v0, v0, v1
	v_cvt_pk_bf16_f32 v1, v6, v7
	v_cvt_pk_bf16_f32 v2, v2, v3
	v_cvt_pk_bf16_f32 v3, v4, v5
	global_store_dwordx4 v[22:23], v[0:3], off offset:2096
	s_barrier
	s_cbranch_scc1 .LBB0_1676
